# item_cmp: the four per-head NSA gate loads issued together at the first head epilogue (were one exposed load per head)
# speedup vs baseline: 1.0006x; 1.0006x over previous
.LBB0_303:
	v_and_b32_e32 v4, 64, v228
	v_xor_b32_e32 v0, 32, v228
	v_add_u32_e32 v197, 64, v4
	v_cmp_lt_i32_e32 vcc, v0, v197
	v_readlane_b32 s0, v253, 4
	v_lshlrev_b64 v[2:3], 6, v[134:135]
	v_cndmask_b32_e32 v0, v228, v0, vcc
	v_lshlrev_b32_e32 v198, 2, v0
	ds_bpermute_b32 v0, v198, v159
	v_readlane_b32 s1, v253, 5
	v_mov_b32_e32 v139, v1
	s_mov_b32 s29, s81
	v_lshl_add_u64 v[142:143], s[0:1], 0, v[2:3]
	s_waitcnt lgkmcnt(0)
	v_add_f32_e32 v0, v159, v0
	v_cmp_lt_f32_e32 vcc, 0, v0
	v_rcp_f32_e32 v0, v0
	v_readlane_b32 s0, v253, 6
	v_readlane_b32 s1, v253, 7
	v_mov_b32_e32 v12, v222
	v_cndmask_b32_e32 v134, 0, v0, vcc
	global_load_ushort v0, v[142:143], off
	global_load_ushort v165, v[142:143], off offset:6
	global_load_ushort v166, v[142:143], off offset:12
	global_load_ushort v167, v[142:143], off offset:18
	v_lshl_add_u64 v[2:3], v[144:145], 1, s[0:1]
	v_lshl_add_u64 v[2:3], v[2:3], 0, v[138:139]
	v_lshl_add_u64 v[144:145], v[2:3], 0, s[28:29]
	s_movk_i32 s0, 0x48
	v_mov_b32_e32 v135, 0
	s_mov_b32 s12, 0
	v_mov_b32_e32 v201, 0xff800000
	s_mov_b32 s13, 0
	s_waitcnt vmcnt(0)
	v_lshlrev_b32_e32 v0, 16, v0
	v_mul_f32_e32 v0, 0xbfb8aa3b, v0
	v_exp_f32_e32 v0, v0
	s_nop 0
	v_add_f32_e32 v0, 1.0, v0
	v_rcp_f32_e32 v0, v0
	s_nop 0
	v_mul_f32_e32 v0, v134, v0
	v_pk_mul_f32 v[2:3], v[50:51], v[0:1] op_sel_hi:[1,0]
	v_pk_mul_f32 v[4:5], v[52:53], v[0:1] op_sel_hi:[1,0]
	v_cvt_pk_bf16_f32 v2, v2, v3
	v_cvt_pk_bf16_f32 v3, v4, v5
	global_store_dwordx2 v[144:145], v[2:3], off
	v_pk_mul_f32 v[2:3], v[54:55], v[0:1] op_sel_hi:[1,0]
	v_pk_mul_f32 v[4:5], v[56:57], v[0:1] op_sel_hi:[1,0]
	v_cvt_pk_bf16_f32 v2, v2, v3
	v_cvt_pk_bf16_f32 v3, v4, v5
	global_store_dwordx2 v[144:145], v[2:3], off offset:16
	v_pk_mul_f32 v[2:3], v[58:59], v[0:1] op_sel_hi:[1,0]
	v_pk_mul_f32 v[4:5], v[60:61], v[0:1] op_sel_hi:[1,0]
	v_cvt_pk_bf16_f32 v2, v2, v3
	v_cvt_pk_bf16_f32 v3, v4, v5
	global_store_dwordx2 v[144:145], v[2:3], off offset:32
	v_pk_mul_f32 v[2:3], v[62:63], v[0:1] op_sel_hi:[1,0]
	v_pk_mul_f32 v[4:5], v[64:65], v[0:1] op_sel_hi:[1,0]
	v_cvt_pk_bf16_f32 v2, v2, v3
	v_cvt_pk_bf16_f32 v3, v4, v5
	global_store_dwordx2 v[144:145], v[2:3], off offset:48
	v_pk_mul_f32 v[2:3], v[34:35], v[0:1] op_sel_hi:[1,0]
	v_pk_mul_f32 v[4:5], v[36:37], v[0:1] op_sel_hi:[1,0]
	v_cvt_pk_bf16_f32 v2, v2, v3
	v_cvt_pk_bf16_f32 v3, v4, v5
	global_store_dwordx2 v[144:145], v[2:3], off offset:64
	v_pk_mul_f32 v[2:3], v[38:39], v[0:1] op_sel_hi:[1,0]
	v_pk_mul_f32 v[4:5], v[40:41], v[0:1] op_sel_hi:[1,0]
	v_cvt_pk_bf16_f32 v2, v2, v3
	v_cvt_pk_bf16_f32 v3, v4, v5
	global_store_dwordx2 v[144:145], v[2:3], off offset:80
	v_pk_mul_f32 v[2:3], v[42:43], v[0:1] op_sel_hi:[1,0]
	v_pk_mul_f32 v[4:5], v[44:45], v[0:1] op_sel_hi:[1,0]
	v_cvt_pk_bf16_f32 v2, v2, v3
	v_cvt_pk_bf16_f32 v3, v4, v5
	global_store_dwordx2 v[144:145], v[2:3], off offset:96
	v_pk_mul_f32 v[2:3], v[46:47], v[0:1] op_sel_hi:[1,0]
	v_pk_mul_f32 v[4:5], v[48:49], v[0:1] op_sel_hi:[1,0]
	v_cvt_pk_bf16_f32 v2, v2, v3
	v_cvt_pk_bf16_f32 v3, v4, v5
	global_store_dwordx2 v[144:145], v[2:3], off offset:112
	global_load_dwordx4 v[98:101], v[132:133], off offset:128
	global_load_dwordx4 v[102:105], v[132:133], off offset:160
	global_load_dwordx4 v[106:109], v[132:133], off offset:192
	global_load_dwordx4 v[110:113], v[132:133], off offset:224
	s_nop 0
	v_ashrrev_i32_e32 v0, 31, v12
	v_lshrrev_b32_e32 v0, 29, v0
	v_add_u32_e32 v0, v12, v0
	v_ashrrev_i32_e32 v6, 3, v0
	v_ashrrev_i32_e32 v7, 31, v6
	v_and_b32_e32 v0, -8, v0
	v_lshlrev_b64 v[2:3], 7, v[6:7]
	v_add_u32_e32 v7, 0x100, v12
	v_sub_u32_e32 v26, v12, v0
	v_ashrrev_i32_e32 v0, 31, v7
	v_lshrrev_b32_e32 v0, 29, v0
	v_lshlrev_b32_e32 v136, 3, v26
	v_add_u32_e32 v0, v7, v0
	v_ashrrev_i32_e32 v137, 31, v136
	v_ashrrev_i32_e32 v14, 3, v0
	v_and_b32_e32 v0, -8, v0
	v_lshl_add_u64 v[8:9], s[24:25], 0, v[2:3]
	v_lshlrev_b64 v[4:5], 1, v[136:137]
	v_sub_u32_e32 v27, v7, v0
	v_lshl_add_u64 v[8:9], v[8:9], 0, v[4:5]
	v_ashrrev_i32_e32 v15, 31, v14
	v_lshlrev_b32_e32 v146, 3, v27
	s_barrier
	global_load_dwordx4 v[114:117], v[8:9], off
	v_lshlrev_b64 v[8:9], 7, v[14:15]
	v_ashrrev_i32_e32 v147, 31, v146
	v_lshl_add_u64 v[16:17], s[24:25], 0, v[8:9]
	v_lshlrev_b64 v[10:11], 1, v[146:147]
	v_lshl_add_u64 v[16:17], v[16:17], 0, v[10:11]
	global_load_dwordx4 v[118:121], v[16:17], off
	v_ashrrev_i32_e32 v16, 3, v12
	v_ashrrev_i32_e32 v17, 31, v16
	v_lshlrev_b32_e32 v0, 3, v12
	v_lshlrev_b64 v[18:19], 10, v[16:17]
	v_and_b32_e32 v0, 56, v0
	v_lshl_add_u64 v[20:21], s[26:27], 0, v[18:19]
	v_lshlrev_b32_e32 v0, 1, v0
	v_lshl_add_u64 v[20:21], v[20:21], 0, v[0:1]
	global_load_dwordx4 v[122:125], v[20:21], off
	v_ashrrev_i32_e32 v20, 3, v7
	v_ashrrev_i32_e32 v21, 31, v20
	v_lshlrev_b64 v[22:23], 10, v[20:21]
	v_lshl_add_u64 v[24:25], s[26:27], 0, v[22:23]
	v_lshl_add_u64 v[24:25], v[24:25], 0, v[0:1]
	global_load_dwordx4 v[126:129], v[24:25], off
	v_mul_lo_u32 v137, v6, s0
	v_lshlrev_b32_e32 v6, 4, v26
	v_lshl_add_u32 v6, v137, 1, v6
	v_mul_lo_u32 v139, v14, s0
	s_movk_i32 s0, 0x44
	v_mul_lo_u32 v147, v16, s0
	v_mul_lo_u32 v156, v20, s0
	v_bfe_u32 v13, v12, 5, 1
	v_lshlrev_b32_e32 v14, 4, v13
	v_lshl_add_u64 v[2:3], v[2:3], 0, v[4:5]
	v_lshlrev_b32_e32 v160, 6, v13
	v_lshl_add_u64 v[154:155], s[34:35], 0, v[2:3]
	v_mov_b32_e32 v50, 0
	v_mov_b32_e32 v51, v135
	v_mov_b32_e32 v52, v135
	v_mov_b32_e32 v53, v135
	v_mov_b32_e32 v54, v135
	v_mov_b32_e32 v55, v135
	v_mov_b32_e32 v56, v135
	v_mov_b32_e32 v57, v135
	v_mov_b32_e32 v58, v135
	v_mov_b32_e32 v59, v135
	v_mov_b32_e32 v60, v135
	v_mov_b32_e32 v61, v135
	v_mov_b32_e32 v62, v135
	v_mov_b32_e32 v63, v135
	v_mov_b32_e32 v64, v135
	v_mov_b32_e32 v65, v135
	v_mov_b32_e32 v34, v135
	v_mov_b32_e32 v35, v135
	v_mov_b32_e32 v36, v135
	v_mov_b32_e32 v37, v135
	v_mov_b32_e32 v38, v135
	v_mov_b32_e32 v39, v135
	v_mov_b32_e32 v40, v135
	v_mov_b32_e32 v41, v135
	v_mov_b32_e32 v42, v135
	v_mov_b32_e32 v43, v135
	v_mov_b32_e32 v44, v135
	v_mov_b32_e32 v45, v135
	v_mov_b32_e32 v46, v135
	v_mov_b32_e32 v47, v135
	v_mov_b32_e32 v48, v135
	v_mov_b32_e32 v49, v135
	s_waitcnt vmcnt(3)
	ds_write_b128 v6, v[114:117]
	v_lshlrev_b32_e32 v6, 4, v27
	v_lshl_add_u32 v6, v139, 1, v6
	s_waitcnt vmcnt(2)
	ds_write_b128 v6, v[118:121]
	v_lshlrev_b32_e32 v6, 1, v147
	v_add3_u32 v6, v6, v0, s93
	s_waitcnt vmcnt(1)
	ds_write2_b64 v6, v[122:123], v[124:125] offset1:1
	v_lshlrev_b32_e32 v6, 1, v156
	v_add3_u32 v6, v6, v0, s93
	s_waitcnt vmcnt(0)
	ds_write2_b64 v6, v[126:127], v[128:129] offset1:1
	v_and_b32_e32 v6, 31, v12
	v_mul_u32_u24_e32 v7, 0x90, v6
	v_mad_u32_u24 v157, v6, s56, v14
	v_lshlrev_b32_e32 v6, 3, v6
	v_sub_u32_e32 v6, v7, v6
	v_lshl_add_u32 v159, v13, 3, v6
	v_lshlrev_b32_e32 v6, 4, v12
	v_and_b32_e32 v6, 0x70, v6
	v_or_b32_e32 v18, v18, v6
	v_or_b32_e32 v22, v22, v6
	v_lshl_add_u64 v[6:7], v[8:9], 0, v[10:11]
	v_lshl_add_u64 v[148:149], s[30:31], 0, v[18:19]
	v_lshl_add_u64 v[150:151], s[30:31], 0, v[22:23]
	v_lshl_add_u64 v[152:153], s[34:35], 0, v[6:7]
	s_waitcnt lgkmcnt(0)
	s_barrier
	s_branch .LBB0_305

.LBB0_327:
	ds_bpermute_b32 v0, v198, v135
	v_mov_b32_e32 v14, v222
	s_movk_i32 s0, 0x48
	v_mov_b32_e32 v139, 0
	v_mov_b32_e32 v202, 0xff800000
	s_waitcnt lgkmcnt(0)
	v_add_f32_e32 v0, v135, v0
	v_cmp_lt_f32_e32 vcc, 0, v0
	v_rcp_f32_e32 v0, v0
	s_mov_b32 s12, 0
	s_mov_b32 s13, 0
	v_cndmask_b32_e32 v135, 0, v0, vcc
	v_mov_b32_e32 v0, v165
	s_waitcnt vmcnt(0)
	v_lshlrev_b32_e32 v0, 16, v0
	v_mul_f32_e32 v0, 0xbfb8aa3b, v0
	v_exp_f32_e32 v0, v0
	s_nop 0
	v_add_f32_e32 v0, 1.0, v0
	v_rcp_f32_e32 v0, v0
	s_nop 0
	v_mul_f32_e32 v0, v135, v0
	v_pk_mul_f32 v[2:3], v[50:51], v[0:1] op_sel_hi:[1,0]
	v_pk_mul_f32 v[4:5], v[52:53], v[0:1] op_sel_hi:[1,0]
	v_cvt_pk_bf16_f32 v2, v2, v3
	v_cvt_pk_bf16_f32 v3, v4, v5
	global_store_dwordx2 v[144:145], v[2:3], off offset:128
	v_pk_mul_f32 v[2:3], v[54:55], v[0:1] op_sel_hi:[1,0]
	v_pk_mul_f32 v[4:5], v[56:57], v[0:1] op_sel_hi:[1,0]
	v_cvt_pk_bf16_f32 v2, v2, v3
	v_cvt_pk_bf16_f32 v3, v4, v5
	global_store_dwordx2 v[144:145], v[2:3], off offset:144
	v_pk_mul_f32 v[2:3], v[58:59], v[0:1] op_sel_hi:[1,0]
	v_pk_mul_f32 v[4:5], v[60:61], v[0:1] op_sel_hi:[1,0]
	v_cvt_pk_bf16_f32 v2, v2, v3
	v_cvt_pk_bf16_f32 v3, v4, v5
	global_store_dwordx2 v[144:145], v[2:3], off offset:160
	v_pk_mul_f32 v[2:3], v[62:63], v[0:1] op_sel_hi:[1,0]
	v_pk_mul_f32 v[4:5], v[64:65], v[0:1] op_sel_hi:[1,0]
	v_cvt_pk_bf16_f32 v2, v2, v3
	v_cvt_pk_bf16_f32 v3, v4, v5
	global_store_dwordx2 v[144:145], v[2:3], off offset:176
	v_pk_mul_f32 v[2:3], v[34:35], v[0:1] op_sel_hi:[1,0]
	v_pk_mul_f32 v[4:5], v[36:37], v[0:1] op_sel_hi:[1,0]
	v_cvt_pk_bf16_f32 v2, v2, v3
	v_cvt_pk_bf16_f32 v3, v4, v5
	global_store_dwordx2 v[144:145], v[2:3], off offset:192
	v_pk_mul_f32 v[2:3], v[38:39], v[0:1] op_sel_hi:[1,0]
	v_pk_mul_f32 v[4:5], v[40:41], v[0:1] op_sel_hi:[1,0]
	v_cvt_pk_bf16_f32 v2, v2, v3
	v_cvt_pk_bf16_f32 v3, v4, v5
	global_store_dwordx2 v[144:145], v[2:3], off offset:208
	v_pk_mul_f32 v[2:3], v[42:43], v[0:1] op_sel_hi:[1,0]
	v_pk_mul_f32 v[4:5], v[44:45], v[0:1] op_sel_hi:[1,0]
	v_cvt_pk_bf16_f32 v2, v2, v3
	v_cvt_pk_bf16_f32 v3, v4, v5
	global_store_dwordx2 v[144:145], v[2:3], off offset:224
	v_pk_mul_f32 v[2:3], v[46:47], v[0:1] op_sel_hi:[1,0]
	v_pk_mul_f32 v[4:5], v[48:49], v[0:1] op_sel_hi:[1,0]
	v_cvt_pk_bf16_f32 v2, v2, v3
	v_cvt_pk_bf16_f32 v3, v4, v5
	global_store_dwordx2 v[144:145], v[2:3], off offset:240
	global_load_dwordx4 v[98:101], v[132:133], off offset:256
	global_load_dwordx4 v[102:105], v[132:133], off offset:288
	global_load_dwordx4 v[106:109], v[132:133], off offset:320
	global_load_dwordx4 v[110:113], v[132:133], off offset:352
	s_nop 0
	v_ashrrev_i32_e32 v0, 31, v14
	v_lshrrev_b32_e32 v0, 29, v0
	v_add_u32_e32 v0, v14, v0
	v_ashrrev_i32_e32 v6, 3, v0
	v_ashrrev_i32_e32 v7, 31, v6
	v_and_b32_e32 v0, -8, v0
	v_lshlrev_b64 v[2:3], 7, v[6:7]
	v_add_u32_e32 v7, 0x100, v14
	v_sub_u32_e32 v26, v14, v0
	v_ashrrev_i32_e32 v0, 31, v7
	v_lshrrev_b32_e32 v0, 29, v0
	v_lshlrev_b32_e32 v136, 3, v26
	v_add_u32_e32 v0, v7, v0
	v_ashrrev_i32_e32 v137, 31, v136
	v_ashrrev_i32_e32 v12, 3, v0
	v_and_b32_e32 v0, -8, v0
	v_lshl_add_u64 v[8:9], s[24:25], 0, v[2:3]
	v_lshlrev_b64 v[4:5], 1, v[136:137]
	v_sub_u32_e32 v27, v7, v0
	v_lshl_add_u64 v[8:9], v[8:9], 0, v[4:5]
	v_ashrrev_i32_e32 v13, 31, v12
	v_lshlrev_b32_e32 v146, 3, v27
	s_barrier
	global_load_dwordx4 v[114:117], v[8:9], off
	v_lshlrev_b64 v[8:9], 7, v[12:13]
	v_ashrrev_i32_e32 v147, 31, v146
	v_lshl_add_u64 v[16:17], s[24:25], 0, v[8:9]
	v_lshlrev_b64 v[10:11], 1, v[146:147]
	v_lshl_add_u64 v[16:17], v[16:17], 0, v[10:11]
	global_load_dwordx4 v[118:121], v[16:17], off
	v_ashrrev_i32_e32 v16, 3, v14
	v_ashrrev_i32_e32 v17, 31, v16
	v_lshlrev_b32_e32 v0, 3, v14
	v_lshlrev_b64 v[18:19], 10, v[16:17]
	v_and_b32_e32 v0, 56, v0
	v_lshl_add_u64 v[20:21], s[26:27], 0, v[18:19]
	v_lshlrev_b32_e32 v0, 1, v0
	v_lshl_add_u64 v[20:21], v[20:21], 0, v[0:1]
	global_load_dwordx4 v[122:125], v[20:21], off
	v_ashrrev_i32_e32 v20, 3, v7
	v_ashrrev_i32_e32 v21, 31, v20
	v_lshlrev_b64 v[22:23], 10, v[20:21]
	v_lshl_add_u64 v[24:25], s[26:27], 0, v[22:23]
	v_lshl_add_u64 v[24:25], v[24:25], 0, v[0:1]
	global_load_dwordx4 v[126:129], v[24:25], off
	v_mul_lo_u32 v137, v6, s0
	v_lshlrev_b32_e32 v6, 4, v26
	v_lshl_add_u32 v6, v137, 1, v6
	v_mul_lo_u32 v147, v12, s0
	s_movk_i32 s0, 0x44
	v_mul_lo_u32 v156, v16, s0
	v_mul_lo_u32 v157, v20, s0
	v_bfe_u32 v15, v14, 5, 1
	v_lshlrev_b32_e32 v12, 4, v15
	v_lshl_add_u64 v[2:3], v[2:3], 0, v[4:5]
	v_lshlrev_b32_e32 v161, 6, v15
	v_lshl_add_u64 v[154:155], s[34:35], 0, v[2:3]
	v_mov_b32_e32 v50, 0
	v_mov_b32_e32 v51, v139
	v_mov_b32_e32 v52, v139
	v_mov_b32_e32 v53, v139
	v_mov_b32_e32 v54, v139
	v_mov_b32_e32 v55, v139
	v_mov_b32_e32 v56, v139
	v_mov_b32_e32 v57, v139
	v_mov_b32_e32 v58, v139
	v_mov_b32_e32 v59, v139
	v_mov_b32_e32 v60, v139
	v_mov_b32_e32 v61, v139
	v_mov_b32_e32 v62, v139
	v_mov_b32_e32 v63, v139
	v_mov_b32_e32 v64, v139
	v_mov_b32_e32 v65, v139
	v_mov_b32_e32 v34, v139
	v_mov_b32_e32 v35, v139
	v_mov_b32_e32 v36, v139
	v_mov_b32_e32 v37, v139
	v_mov_b32_e32 v38, v139
	v_mov_b32_e32 v39, v139
	v_mov_b32_e32 v40, v139
	v_mov_b32_e32 v41, v139
	v_mov_b32_e32 v42, v139
	v_mov_b32_e32 v43, v139
	v_mov_b32_e32 v44, v139
	v_mov_b32_e32 v45, v139
	v_mov_b32_e32 v46, v139
	v_mov_b32_e32 v47, v139
	v_mov_b32_e32 v48, v139
	v_mov_b32_e32 v49, v139
	s_waitcnt vmcnt(3)
	ds_write_b128 v6, v[114:117]
	v_lshlrev_b32_e32 v6, 4, v27
	v_lshl_add_u32 v6, v147, 1, v6
	s_waitcnt vmcnt(2)
	ds_write_b128 v6, v[118:121]
	v_lshlrev_b32_e32 v6, 1, v156
	v_add3_u32 v6, v6, v0, s93
	s_waitcnt vmcnt(1)
	ds_write2_b64 v6, v[122:123], v[124:125] offset1:1
	v_lshlrev_b32_e32 v6, 1, v157
	v_add3_u32 v6, v6, v0, s93
	s_waitcnt vmcnt(0)
	ds_write2_b64 v6, v[126:127], v[128:129] offset1:1
	v_and_b32_e32 v6, 31, v14
	v_mul_u32_u24_e32 v7, 0x90, v6
	v_mad_u32_u24 v159, v6, s56, v12
	v_lshlrev_b32_e32 v6, 3, v6
	v_sub_u32_e32 v6, v7, v6
	v_lshl_add_u32 v160, v15, 3, v6
	v_lshlrev_b32_e32 v6, 4, v14
	v_and_b32_e32 v6, 0x70, v6
	v_or_b32_e32 v18, v18, v6
	v_or_b32_e32 v22, v22, v6
	v_lshl_add_u64 v[6:7], v[8:9], 0, v[10:11]
	v_lshl_add_u64 v[148:149], s[30:31], 0, v[18:19]
	v_lshl_add_u64 v[150:151], s[30:31], 0, v[22:23]
	v_lshl_add_u64 v[152:153], s[34:35], 0, v[6:7]
	s_waitcnt lgkmcnt(0)
	s_barrier
	s_branch .LBB0_329

.LBB0_351:
	ds_bpermute_b32 v0, v198, v139
	v_mov_b32_e32 v14, v222
	s_movk_i32 s0, 0x48
	v_mov_b32_e32 v137, 0
	v_mov_b32_e32 v203, 0xff800000
	s_waitcnt lgkmcnt(0)
	v_add_f32_e32 v0, v139, v0
	v_cmp_lt_f32_e32 vcc, 0, v0
	v_rcp_f32_e32 v0, v0
	s_mov_b32 s12, 0
	s_mov_b32 s13, 0
	v_cndmask_b32_e32 v136, 0, v0, vcc
	v_mov_b32_e32 v0, v166
	s_waitcnt vmcnt(0)
	v_lshlrev_b32_e32 v0, 16, v0
	v_mul_f32_e32 v0, 0xbfb8aa3b, v0
	v_exp_f32_e32 v0, v0
	s_nop 0
	v_add_f32_e32 v0, 1.0, v0
	v_rcp_f32_e32 v0, v0
	s_nop 0
	v_mul_f32_e32 v0, v136, v0
	v_pk_mul_f32 v[2:3], v[50:51], v[0:1] op_sel_hi:[1,0]
	v_pk_mul_f32 v[4:5], v[52:53], v[0:1] op_sel_hi:[1,0]
	v_cvt_pk_bf16_f32 v2, v2, v3
	v_cvt_pk_bf16_f32 v3, v4, v5
	global_store_dwordx2 v[144:145], v[2:3], off offset:256
	v_pk_mul_f32 v[2:3], v[54:55], v[0:1] op_sel_hi:[1,0]
	v_pk_mul_f32 v[4:5], v[56:57], v[0:1] op_sel_hi:[1,0]
	v_cvt_pk_bf16_f32 v2, v2, v3
	v_cvt_pk_bf16_f32 v3, v4, v5
	global_store_dwordx2 v[144:145], v[2:3], off offset:272
	v_pk_mul_f32 v[2:3], v[58:59], v[0:1] op_sel_hi:[1,0]
	v_pk_mul_f32 v[4:5], v[60:61], v[0:1] op_sel_hi:[1,0]
	v_cvt_pk_bf16_f32 v2, v2, v3
	v_cvt_pk_bf16_f32 v3, v4, v5
	global_store_dwordx2 v[144:145], v[2:3], off offset:288
	v_pk_mul_f32 v[2:3], v[62:63], v[0:1] op_sel_hi:[1,0]
	v_pk_mul_f32 v[4:5], v[64:65], v[0:1] op_sel_hi:[1,0]
	v_cvt_pk_bf16_f32 v2, v2, v3
	v_cvt_pk_bf16_f32 v3, v4, v5
	global_store_dwordx2 v[144:145], v[2:3], off offset:304
	v_pk_mul_f32 v[2:3], v[34:35], v[0:1] op_sel_hi:[1,0]
	v_pk_mul_f32 v[4:5], v[36:37], v[0:1] op_sel_hi:[1,0]
	v_cvt_pk_bf16_f32 v2, v2, v3
	v_cvt_pk_bf16_f32 v3, v4, v5
	global_store_dwordx2 v[144:145], v[2:3], off offset:320
	v_pk_mul_f32 v[2:3], v[38:39], v[0:1] op_sel_hi:[1,0]
	v_pk_mul_f32 v[4:5], v[40:41], v[0:1] op_sel_hi:[1,0]
	v_cvt_pk_bf16_f32 v2, v2, v3
	v_cvt_pk_bf16_f32 v3, v4, v5
	global_store_dwordx2 v[144:145], v[2:3], off offset:336
	v_pk_mul_f32 v[2:3], v[42:43], v[0:1] op_sel_hi:[1,0]
	v_pk_mul_f32 v[4:5], v[44:45], v[0:1] op_sel_hi:[1,0]
	v_cvt_pk_bf16_f32 v2, v2, v3
	v_cvt_pk_bf16_f32 v3, v4, v5
	global_store_dwordx2 v[144:145], v[2:3], off offset:352
	v_pk_mul_f32 v[2:3], v[46:47], v[0:1] op_sel_hi:[1,0]
	v_pk_mul_f32 v[4:5], v[48:49], v[0:1] op_sel_hi:[1,0]
	v_cvt_pk_bf16_f32 v2, v2, v3
	v_cvt_pk_bf16_f32 v3, v4, v5
	global_store_dwordx2 v[144:145], v[2:3], off offset:368
	global_load_dwordx4 v[98:101], v[132:133], off offset:384
	global_load_dwordx4 v[102:105], v[132:133], off offset:416
	global_load_dwordx4 v[106:109], v[132:133], off offset:448
	global_load_dwordx4 v[110:113], v[132:133], off offset:480
	s_nop 0
	v_ashrrev_i32_e32 v0, 31, v14
	v_lshrrev_b32_e32 v0, 29, v0
	v_add_u32_e32 v0, v14, v0
	v_ashrrev_i32_e32 v6, 3, v0
	v_ashrrev_i32_e32 v7, 31, v6
	v_and_b32_e32 v0, -8, v0
	v_lshlrev_b64 v[2:3], 7, v[6:7]
	v_add_u32_e32 v7, 0x100, v14
	v_sub_u32_e32 v26, v14, v0
	v_ashrrev_i32_e32 v0, 31, v7
	v_lshrrev_b32_e32 v0, 29, v0
	v_lshlrev_b32_e32 v146, 3, v26
	v_add_u32_e32 v0, v7, v0
	v_ashrrev_i32_e32 v147, 31, v146
	v_ashrrev_i32_e32 v12, 3, v0
	v_and_b32_e32 v0, -8, v0
	v_lshl_add_u64 v[8:9], s[24:25], 0, v[2:3]
	v_lshlrev_b64 v[4:5], 1, v[146:147]
	v_sub_u32_e32 v27, v7, v0
	v_lshl_add_u64 v[8:9], v[8:9], 0, v[4:5]
	v_ashrrev_i32_e32 v13, 31, v12
	v_lshlrev_b32_e32 v148, 3, v27
	s_barrier
	global_load_dwordx4 v[114:117], v[8:9], off
	v_lshlrev_b64 v[8:9], 7, v[12:13]
	v_ashrrev_i32_e32 v149, 31, v148
	v_lshl_add_u64 v[16:17], s[24:25], 0, v[8:9]
	v_lshlrev_b64 v[10:11], 1, v[148:149]
	v_lshl_add_u64 v[16:17], v[16:17], 0, v[10:11]
	global_load_dwordx4 v[118:121], v[16:17], off
	v_ashrrev_i32_e32 v16, 3, v14
	v_ashrrev_i32_e32 v17, 31, v16
	v_lshlrev_b32_e32 v0, 3, v14
	v_lshlrev_b64 v[18:19], 10, v[16:17]
	v_and_b32_e32 v0, 56, v0
	v_lshl_add_u64 v[20:21], s[26:27], 0, v[18:19]
	v_lshlrev_b32_e32 v0, 1, v0
	v_lshl_add_u64 v[20:21], v[20:21], 0, v[0:1]
	global_load_dwordx4 v[122:125], v[20:21], off
	v_ashrrev_i32_e32 v20, 3, v7
	v_ashrrev_i32_e32 v21, 31, v20
	v_lshlrev_b64 v[22:23], 10, v[20:21]
	v_lshl_add_u64 v[24:25], s[26:27], 0, v[22:23]
	v_lshl_add_u64 v[24:25], v[24:25], 0, v[0:1]
	global_load_dwordx4 v[126:129], v[24:25], off
	v_mul_lo_u32 v139, v6, s0
	v_lshlrev_b32_e32 v6, 4, v26
	v_lshl_add_u32 v6, v139, 1, v6
	v_mul_lo_u32 v147, v12, s0
	s_movk_i32 s0, 0x44
	v_mul_lo_u32 v149, v16, s0
	v_mul_lo_u32 v159, v20, s0
	v_bfe_u32 v15, v14, 5, 1
	v_lshlrev_b32_e32 v12, 4, v15
	v_lshl_add_u64 v[2:3], v[2:3], 0, v[4:5]
	v_lshlrev_b32_e32 v162, 6, v15
	v_lshl_add_u64 v[156:157], s[34:35], 0, v[2:3]
	v_mov_b32_e32 v50, 0
	v_mov_b32_e32 v51, v137
	v_mov_b32_e32 v52, v137
	v_mov_b32_e32 v53, v137
	v_mov_b32_e32 v54, v137
	v_mov_b32_e32 v55, v137
	v_mov_b32_e32 v56, v137
	v_mov_b32_e32 v57, v137
	v_mov_b32_e32 v58, v137
	v_mov_b32_e32 v59, v137
	v_mov_b32_e32 v60, v137
	v_mov_b32_e32 v61, v137
	v_mov_b32_e32 v62, v137
	v_mov_b32_e32 v63, v137
	v_mov_b32_e32 v64, v137
	v_mov_b32_e32 v65, v137
	v_mov_b32_e32 v34, v137
	v_mov_b32_e32 v35, v137
	v_mov_b32_e32 v36, v137
	v_mov_b32_e32 v37, v137
	v_mov_b32_e32 v38, v137
	v_mov_b32_e32 v39, v137
	v_mov_b32_e32 v40, v137
	v_mov_b32_e32 v41, v137
	v_mov_b32_e32 v42, v137
	v_mov_b32_e32 v43, v137
	v_mov_b32_e32 v44, v137
	v_mov_b32_e32 v45, v137
	v_mov_b32_e32 v46, v137
	v_mov_b32_e32 v47, v137
	v_mov_b32_e32 v48, v137
	v_mov_b32_e32 v49, v137
	s_waitcnt vmcnt(3)
	ds_write_b128 v6, v[114:117]
	v_lshlrev_b32_e32 v6, 4, v27
	v_lshl_add_u32 v6, v147, 1, v6
	s_waitcnt vmcnt(2)
	ds_write_b128 v6, v[118:121]
	v_lshlrev_b32_e32 v6, 1, v149
	v_add3_u32 v6, v6, v0, s93
	s_waitcnt vmcnt(1)
	ds_write2_b64 v6, v[122:123], v[124:125] offset1:1
	v_lshlrev_b32_e32 v6, 1, v159
	v_add3_u32 v6, v6, v0, s93
	s_waitcnt vmcnt(0)
	ds_write2_b64 v6, v[126:127], v[128:129] offset1:1
	v_and_b32_e32 v6, 31, v14
	v_mul_u32_u24_e32 v7, 0x90, v6
	v_mad_u32_u24 v160, v6, s56, v12
	v_lshlrev_b32_e32 v6, 3, v6
	v_sub_u32_e32 v6, v7, v6
	v_lshl_add_u32 v161, v15, 3, v6
	v_lshlrev_b32_e32 v6, 4, v14
	v_and_b32_e32 v6, 0x70, v6
	v_or_b32_e32 v18, v18, v6
	v_or_b32_e32 v22, v22, v6
	v_lshl_add_u64 v[6:7], v[8:9], 0, v[10:11]
	v_lshl_add_u64 v[150:151], s[30:31], 0, v[18:19]
	v_lshl_add_u64 v[152:153], s[30:31], 0, v[22:23]
	v_lshl_add_u64 v[154:155], s[34:35], 0, v[6:7]
	s_waitcnt lgkmcnt(0)
	s_barrier
	s_branch .LBB0_353

.LBB0_375:
	ds_bpermute_b32 v0, v198, v137
	v_mov_b32_e32 v18, 0
	v_lshlrev_b32_e32 v79, 6, v196
	v_mov_b32_e32 v19, 0
	v_mov_b32_e32 v20, 0
	s_waitcnt lgkmcnt(0)
	v_add_f32_e32 v0, v137, v0
	v_cmp_lt_f32_e32 vcc, 0, v0
	v_rcp_f32_e32 v0, v0
	v_mov_b32_e32 v21, 0
	v_mov_b32_e32 v22, 0
	v_mov_b32_e32 v23, 0
	v_cndmask_b32_e32 v78, 0, v0, vcc
	v_mov_b32_e32 v0, v167
	v_cmp_lt_i32_e32 vcc, -1, v199
	v_mov_b32_e32 v24, 0
	v_mov_b32_e32 v25, 0
	v_mov_b32_e32 v26, 0
	v_mov_b32_e32 v27, 0
	v_mov_b32_e32 v28, 0
	v_mov_b32_e32 v29, 0
	v_mov_b32_e32 v30, 0
	v_mov_b32_e32 v31, 0
	v_mov_b32_e32 v32, 0
	v_mov_b32_e32 v33, 0
	v_mov_b32_e32 v10, 0
	v_mov_b32_e32 v11, 0
	v_mov_b32_e32 v12, 0
	v_mov_b32_e32 v13, 0
	v_mov_b32_e32 v14, 0
	v_mov_b32_e32 v15, 0
	v_mov_b32_e32 v16, 0
	s_waitcnt vmcnt(0)
	v_lshlrev_b32_e32 v0, 16, v0
	v_mul_f32_e32 v0, 0xbfb8aa3b, v0
	v_exp_f32_e32 v0, v0
	s_nop 0
	v_add_f32_e32 v0, 1.0, v0
	v_rcp_f32_e32 v0, v0
	s_nop 0
	v_mul_f32_e32 v0, v78, v0
	v_pk_mul_f32 v[2:3], v[50:51], v[0:1] op_sel_hi:[1,0]
	v_pk_mul_f32 v[4:5], v[52:53], v[0:1] op_sel_hi:[1,0]
	v_cvt_pk_bf16_f32 v2, v2, v3
	v_cvt_pk_bf16_f32 v3, v4, v5
	global_store_dwordx2 v[144:145], v[2:3], off offset:384
	v_pk_mul_f32 v[2:3], v[54:55], v[0:1] op_sel_hi:[1,0]
	v_pk_mul_f32 v[4:5], v[56:57], v[0:1] op_sel_hi:[1,0]
	v_cvt_pk_bf16_f32 v2, v2, v3
	v_cvt_pk_bf16_f32 v3, v4, v5
	global_store_dwordx2 v[144:145], v[2:3], off offset:400
	v_pk_mul_f32 v[2:3], v[58:59], v[0:1] op_sel_hi:[1,0]
	v_pk_mul_f32 v[4:5], v[60:61], v[0:1] op_sel_hi:[1,0]
	v_cvt_pk_bf16_f32 v2, v2, v3
	v_cvt_pk_bf16_f32 v3, v4, v5
	global_store_dwordx2 v[144:145], v[2:3], off offset:416
	v_pk_mul_f32 v[2:3], v[62:63], v[0:1] op_sel_hi:[1,0]
	v_pk_mul_f32 v[4:5], v[64:65], v[0:1] op_sel_hi:[1,0]
	v_cvt_pk_bf16_f32 v2, v2, v3
	v_cvt_pk_bf16_f32 v3, v4, v5
	global_store_dwordx2 v[144:145], v[2:3], off offset:432
	v_pk_mul_f32 v[2:3], v[34:35], v[0:1] op_sel_hi:[1,0]
	v_pk_mul_f32 v[4:5], v[36:37], v[0:1] op_sel_hi:[1,0]
	v_cvt_pk_bf16_f32 v2, v2, v3
	v_cvt_pk_bf16_f32 v3, v4, v5
	global_store_dwordx2 v[144:145], v[2:3], off offset:448
	v_pk_mul_f32 v[2:3], v[38:39], v[0:1] op_sel_hi:[1,0]
	v_pk_mul_f32 v[4:5], v[40:41], v[0:1] op_sel_hi:[1,0]
	v_cvt_pk_bf16_f32 v2, v2, v3
	v_cvt_pk_bf16_f32 v3, v4, v5
	global_store_dwordx2 v[144:145], v[2:3], off offset:464
	v_pk_mul_f32 v[2:3], v[42:43], v[0:1] op_sel_hi:[1,0]
	v_pk_mul_f32 v[4:5], v[44:45], v[0:1] op_sel_hi:[1,0]
	v_cvt_pk_bf16_f32 v2, v2, v3
	v_cvt_pk_bf16_f32 v3, v4, v5
	global_store_dwordx2 v[144:145], v[2:3], off offset:480
	v_pk_mul_f32 v[2:3], v[46:47], v[0:1] op_sel_hi:[1,0]
	v_pk_mul_f32 v[4:5], v[48:49], v[0:1] op_sel_hi:[1,0]
	v_cvt_pk_bf16_f32 v2, v2, v3
	v_cvt_pk_bf16_f32 v3, v4, v5
	global_store_dwordx2 v[144:145], v[2:3], off offset:496
	v_lshlrev_b32_e32 v2, 1, v138
	v_lshlrev_b32_e32 v0, 4, v141
	v_mad_u32_u24 v131, v208, s56, v2
	v_ashrrev_i32_e32 v2, 3, v141
	v_and_b32_e32 v0, 0x70, v0
	v_mul_lo_u32 v4, v2, s56
	v_ashrrev_i32_e32 v3, 31, v2
	v_add_u32_e32 v204, v0, v4
	v_add_u32_e32 v4, 0x100, v141
	v_lshl_add_u64 v[6:7], s[24:25], 0, v[0:1]
	v_ashrrev_i32_e32 v8, 3, v4
	v_lshlrev_b64 v[2:3], 7, v[2:3]
	v_mul_lo_u32 v4, v8, s56
	v_lshl_add_u64 v[80:81], v[6:7], 0, v[2:3]
	v_add_u32_e32 v205, v0, v4
	s_barrier
	global_load_dwordx4 v[2:5], v[80:81], off
	v_ashrrev_i32_e32 v9, 31, v8
	v_mov_b32_e32 v0, 0
	s_waitcnt vmcnt(0)
	ds_write_b128 v204, v[2:5]
	v_lshlrev_b64 v[2:3], 7, v[8:9]
	v_lshl_add_u64 v[82:83], v[6:7], 0, v[2:3]
	global_load_dwordx4 v[2:5], v[82:83], off
	v_mov_b32_e32 v6, 0
	v_mov_b32_e32 v7, 0
	v_mov_b32_e32 v8, 0
	v_mov_b32_e32 v9, 0
	s_waitcnt vmcnt(0)
	ds_write_b128 v205, v[2:5]
	v_mov_b32_e32 v2, 0
	v_mov_b32_e32 v3, 0
	v_mov_b32_e32 v4, 0
	v_mov_b32_e32 v5, 0
	s_waitcnt lgkmcnt(0)
	s_barrier
	s_and_saveexec_b64 s[0:1], vcc
	s_cbranch_execz .LBB0_377
	global_load_dwordx4 v[2:5], v[132:133], off
	global_load_dwordx4 v[34:37], v[132:133], off offset:32
	global_load_dwordx4 v[38:41], v[132:133], off offset:64
	global_load_dwordx4 v[66:69], v[132:133], off offset:96
	ds_read_b128 v[58:61], v131 offset:4608
	ds_read_b128 v[62:65], v131
	ds_read_b128 v[54:57], v131 offset:32
	ds_read_b128 v[50:53], v131 offset:4640
	ds_read_b128 v[46:49], v131 offset:64
	ds_read_b128 v[42:45], v131 offset:4672
	v_or_b32_e32 v137, 0x19f, v79
	v_or_b32_e32 v247, 31, v79
	v_or_b32_e32 v246, 47, v79
	v_cmp_le_i32_e32 vcc, v247, v130
	v_add_u32_e32 v245, 63, v79
	v_add_u32_e32 v244, 0x4f, v79
	v_or_b32_e32 v243, 0x9f, v79
	v_or_b32_e32 v242, 0xaf, v79
	v_add_u32_e32 v241, 0xbf, v79
	v_add_u32_e32 v240, 0xcf, v79
	v_or_b32_e32 v239, 0x11f, v79
	v_or_b32_e32 v181, 0x12f, v79
	v_add_u32_e32 v179, 0x13f, v79
	v_add_u32_e32 v143, 0x14f, v79
	v_or_b32_e32 v101, 0x1af, v79
	v_add_u32_e32 v238, 0x1bf, v79
	v_add_u32_e32 v237, 0x1cf, v79
	v_or_b32_e32 v163, 0x21f, v79
	v_or_b32_e32 v161, 0x22f, v79
	v_add_u32_e32 v236, 0x23f, v79
	v_add_u32_e32 v221, 0x24f, v79
	v_or_b32_e32 v220, 0x29f, v79
	v_or_b32_e32 v219, 0x2af, v79
	v_add_u32_e32 v218, 0x2bf, v79
	v_add_u32_e32 v217, 0x2cf, v79
	v_or_b32_e32 v216, 0x31f, v79
	v_or_b32_e32 v215, 0x32f, v79
	v_add_u32_e32 v213, 0x33f, v79
	v_add_u32_e32 v211, 0x34f, v79
	v_or_b32_e32 v117, 0x39f, v79
	v_or_b32_e32 v85, 0x3af, v79
	v_add_u32_e32 v207, 0x3bf, v79
	v_add_u32_e32 v206, 0x3cf, v79
	s_waitcnt vmcnt(3) lgkmcnt(4)
	v_mfma_f32_32x32x16_bf16 v[18:33], v[62:65], v[2:5], 0
	v_mfma_f32_32x32x16_bf16 v[2:17], v[58:61], v[2:5], 0
	s_waitcnt vmcnt(2) lgkmcnt(3)
	v_mfma_f32_32x32x16_bf16 v[18:33], v[54:57], v[34:37], v[18:33]
	s_waitcnt lgkmcnt(2)
	v_mfma_f32_32x32x16_bf16 v[2:17], v[50:53], v[34:37], v[2:17]
	s_waitcnt vmcnt(1) lgkmcnt(1)
	v_mfma_f32_32x32x16_bf16 v[18:33], v[46:49], v[38:41], v[18:33]
	s_waitcnt lgkmcnt(0)
	v_mfma_f32_32x32x16_bf16 v[2:17], v[42:45], v[38:41], v[2:17]
	ds_read_b128 v[38:41], v131 offset:96
	ds_read_b128 v[34:37], v131 offset:4704
	s_waitcnt vmcnt(0) lgkmcnt(1)
	v_mfma_f32_32x32x16_bf16 v[18:33], v[38:41], v[66:69], v[18:33]
	s_waitcnt lgkmcnt(0)
	v_mfma_f32_32x32x16_bf16 v[2:17], v[34:37], v[66:69], v[2:17]
	s_nop 9
	v_fma_f32 v0, v18, s92, -v200
	v_exp_f32_e32 v114, v0
	v_fma_f32 v0, v19, s92, -v200
	v_exp_f32_e32 v115, v0
	v_fma_f32 v0, v20, s92, -v200
	v_exp_f32_e32 v112, v0
	v_fma_f32 v0, v21, s92, -v200
	v_exp_f32_e32 v113, v0
	v_fma_f32 v0, v22, s92, -v200
	v_exp_f32_e32 v110, v0
	v_fma_f32 v0, v23, s92, -v200
	v_exp_f32_e32 v111, v0
	v_fma_f32 v0, v24, s92, -v200
	v_exp_f32_e32 v108, v0
	v_fma_f32 v0, v25, s92, -v200
	v_exp_f32_e32 v109, v0
	v_fma_f32 v0, v26, s92, -v200
	v_exp_f32_e32 v106, v0
	v_fma_f32 v0, v27, s92, -v200
	v_exp_f32_e32 v107, v0
	v_fma_f32 v0, v28, s92, -v200
	v_exp_f32_e32 v104, v0
	v_fma_f32 v0, v29, s92, -v200
	v_exp_f32_e32 v105, v0
	v_fma_f32 v0, v30, s92, -v200
	v_exp_f32_e32 v102, v0
	v_fma_f32 v0, v31, s92, -v200
	v_exp_f32_e32 v103, v0
	v_fma_f32 v0, v32, s92, -v200
	v_exp_f32_e32 v0, v0
	s_nop 0
	v_mul_f32_e32 v100, v134, v0
	v_fma_f32 v0, v33, s92, -v200
	v_exp_f32_e32 v66, v0
	v_fma_f32 v0, v2, s92, -v200
	v_exp_f32_e32 v98, v0
	v_fma_f32 v0, v3, s92, -v200
	v_exp_f32_e32 v99, v0
	v_fma_f32 v0, v4, s92, -v200
	v_exp_f32_e32 v96, v0
	v_fma_f32 v0, v5, s92, -v200
	global_load_dwordx4 v[2:5], v[132:133], off offset:128
	global_load_dwordx4 v[70:73], v[132:133], off offset:160
	global_load_dwordx4 v[74:77], v[132:133], off offset:192
	global_load_dwordx4 v[118:121], v[132:133], off offset:224
	v_exp_f32_e32 v97, v0
	v_fma_f32 v0, v6, s92, -v200
	v_exp_f32_e32 v94, v0
	v_fma_f32 v0, v7, s92, -v200
	v_exp_f32_e32 v95, v0
	v_fma_f32 v0, v8, s92, -v200
	v_exp_f32_e32 v92, v0
	v_fma_f32 v0, v9, s92, -v200
	v_exp_f32_e32 v93, v0
	v_fma_f32 v0, v10, s92, -v200
	v_exp_f32_e32 v90, v0
	v_fma_f32 v0, v11, s92, -v200
	v_exp_f32_e32 v91, v0
	v_fma_f32 v0, v12, s92, -v200
	v_exp_f32_e32 v88, v0
	v_fma_f32 v0, v13, s92, -v200
	v_exp_f32_e32 v89, v0
	v_fma_f32 v0, v14, s92, -v200
	v_exp_f32_e32 v86, v0
	v_fma_f32 v0, v15, s92, -v200
	v_exp_f32_e32 v87, v0
	v_fma_f32 v0, v16, s92, -v200
	v_exp_f32_e32 v0, v0
	s_waitcnt vmcnt(3)
	v_mfma_f32_32x32x16_bf16 v[18:33], v[62:65], v[2:5], 0
	v_mul_f32_e32 v84, v134, v0
	v_fma_f32 v0, v17, s92, -v200
	v_exp_f32_e32 v68, v0
	s_waitcnt vmcnt(2)
	v_mfma_f32_32x32x16_bf16 v[18:33], v[54:57], v[70:73], v[18:33]
	s_waitcnt vmcnt(1)
	v_mfma_f32_32x32x16_bf16 v[18:33], v[46:49], v[74:77], v[18:33]
	v_mfma_f32_32x32x16_bf16 v[2:17], v[58:61], v[2:5], 0
	s_waitcnt vmcnt(0)
	v_mfma_f32_32x32x16_bf16 v[18:33], v[38:41], v[118:121], v[18:33]
	v_mfma_f32_32x32x16_bf16 v[2:17], v[50:53], v[70:73], v[2:17]
	s_nop 10
	v_fma_f32 v0, v18, s92, -v201
	v_exp_f32_e32 v158, v0
	v_fma_f32 v0, v19, s92, -v201
	v_exp_f32_e32 v159, v0
	v_fma_f32 v0, v20, s92, -v201
	v_exp_f32_e32 v156, v0
	v_fma_f32 v0, v21, s92, -v201
	v_mfma_f32_32x32x16_bf16 v[2:17], v[42:45], v[74:77], v[2:17]
	v_exp_f32_e32 v157, v0
	v_fma_f32 v0, v22, s92, -v201
	v_exp_f32_e32 v154, v0
	v_fma_f32 v0, v23, s92, -v201
	v_exp_f32_e32 v155, v0
	v_fma_f32 v0, v24, s92, -v201
	v_exp_f32_e32 v152, v0
	v_fma_f32 v0, v25, s92, -v201
	v_exp_f32_e32 v153, v0
	v_fma_f32 v0, v26, s92, -v201
	v_exp_f32_e32 v150, v0
	v_fma_f32 v0, v27, s92, -v201
	v_exp_f32_e32 v151, v0
	v_fma_f32 v0, v28, s92, -v201
	v_exp_f32_e32 v148, v0
	v_fma_f32 v0, v29, s92, -v201
	v_mfma_f32_32x32x16_bf16 v[2:17], v[34:37], v[118:121], v[2:17]
	v_exp_f32_e32 v149, v0
	v_fma_f32 v0, v30, s92, -v201
	v_exp_f32_e32 v146, v0
	v_fma_f32 v0, v31, s92, -v201
	v_exp_f32_e32 v147, v0
	v_fma_f32 v0, v32, s92, -v201
	v_exp_f32_e32 v0, v0
	s_nop 0
	v_mul_f32_e32 v142, v135, v0
	v_fma_f32 v0, v33, s92, -v201
	v_exp_f32_e32 v67, v0
	s_nop 0
	v_fma_f32 v0, v2, s92, -v201
	v_exp_f32_e32 v140, v0
	v_fma_f32 v0, v3, s92, -v201
	v_exp_f32_e32 v141, v0
	v_fma_f32 v0, v4, s92, -v201
	v_exp_f32_e32 v138, v0
	v_fma_f32 v0, v5, s92, -v201
	v_exp_f32_e32 v139, v0
	v_fma_f32 v0, v6, s92, -v201
	v_exp_f32_e32 v128, v0
	v_fma_f32 v0, v7, s92, -v201
	v_exp_f32_e32 v129, v0
	v_fma_f32 v0, v8, s92, -v201
	v_exp_f32_e32 v126, v0
	v_fma_f32 v0, v9, s92, -v201
	v_exp_f32_e32 v127, v0
	v_fma_f32 v0, v10, s92, -v201
	v_exp_f32_e32 v124, v0
	v_fma_f32 v0, v11, s92, -v201
	v_exp_f32_e32 v125, v0
	v_fma_f32 v0, v12, s92, -v201
	v_exp_f32_e32 v122, v0
	v_fma_f32 v0, v13, s92, -v201
	v_exp_f32_e32 v123, v0
	v_fma_f32 v0, v14, s92, -v201
	v_exp_f32_e32 v120, v0
	v_fma_f32 v0, v15, s92, -v201
	v_exp_f32_e32 v121, v0
	v_fma_f32 v0, v16, s92, -v201
	v_exp_f32_e32 v0, v0
	v_pk_mul_f32 v[144:145], v[134:135], v[66:67]
	v_mul_f32_e32 v116, v135, v0
	v_fma_f32 v0, v17, s92, -v201
	v_exp_f32_e32 v69, v0
	s_nop 0
	v_pk_mul_f32 v[118:119], v[134:135], v[68:69]
	global_load_dwordx4 v[2:5], v[132:133], off offset:256
	global_load_dwordx4 v[70:73], v[132:133], off offset:288
	global_load_dwordx4 v[66:69], v[132:133], off offset:320
	global_load_dwordx4 v[74:77], v[132:133], off offset:352
	s_waitcnt vmcnt(3)
	v_mfma_f32_32x32x16_bf16 v[18:33], v[62:65], v[2:5], 0
	s_waitcnt vmcnt(2)
	v_mfma_f32_32x32x16_bf16 v[18:33], v[54:57], v[70:73], v[18:33]
	s_waitcnt vmcnt(1)
	v_mfma_f32_32x32x16_bf16 v[18:33], v[46:49], v[66:69], v[18:33]
	v_mfma_f32_32x32x16_bf16 v[2:17], v[58:61], v[2:5], 0
	s_waitcnt vmcnt(0)
	v_mfma_f32_32x32x16_bf16 v[18:33], v[38:41], v[74:77], v[18:33]
	v_mfma_f32_32x32x16_bf16 v[2:17], v[50:53], v[70:73], v[2:17]
	s_nop 10
	v_fma_f32 v0, v18, s92, -v202
	v_exp_f32_e32 v194, v0
	v_fma_f32 v0, v19, s92, -v202
	v_exp_f32_e32 v195, v0
	v_fma_f32 v0, v20, s92, -v202
	v_exp_f32_e32 v192, v0
	v_fma_f32 v0, v21, s92, -v202
	v_mfma_f32_32x32x16_bf16 v[2:17], v[42:45], v[66:69], v[2:17]
	v_exp_f32_e32 v193, v0
	v_fma_f32 v0, v22, s92, -v202
	v_exp_f32_e32 v190, v0
	v_fma_f32 v0, v23, s92, -v202
	v_exp_f32_e32 v191, v0
	v_fma_f32 v0, v24, s92, -v202
	v_exp_f32_e32 v188, v0
	v_fma_f32 v0, v25, s92, -v202
	v_exp_f32_e32 v189, v0
	v_fma_f32 v0, v26, s92, -v202
	v_exp_f32_e32 v186, v0
	v_fma_f32 v0, v27, s92, -v202
	v_exp_f32_e32 v187, v0
	v_fma_f32 v0, v28, s92, -v202
	v_exp_f32_e32 v184, v0
	v_fma_f32 v0, v29, s92, -v202
	v_mfma_f32_32x32x16_bf16 v[2:17], v[34:37], v[74:77], v[2:17]
	v_exp_f32_e32 v185, v0
	v_fma_f32 v0, v30, s92, -v202
	v_exp_f32_e32 v182, v0
	v_fma_f32 v0, v31, s92, -v202
	v_exp_f32_e32 v183, v0
	v_fma_f32 v0, v32, s92, -v202
	v_exp_f32_e32 v0, v0
	s_nop 0
	v_mul_f32_e32 v178, v136, v0
	v_fma_f32 v0, v33, s92, -v202
	v_exp_f32_e32 v180, v0
	s_nop 0
	v_fma_f32 v0, v2, s92, -v202
	v_exp_f32_e32 v176, v0
	v_fma_f32 v0, v3, s92, -v202
	v_exp_f32_e32 v177, v0
	v_fma_f32 v0, v4, s92, -v202
	v_exp_f32_e32 v174, v0
	v_fma_f32 v0, v5, s92, -v202
	global_load_dwordx4 v[2:5], v[132:133], off offset:384
	global_load_dwordx4 v[66:69], v[132:133], off offset:416
	global_load_dwordx4 v[70:73], v[132:133], off offset:448
	global_load_dwordx4 v[74:77], v[132:133], off offset:480
	v_exp_f32_e32 v175, v0
	v_fma_f32 v0, v6, s92, -v202
	v_exp_f32_e32 v172, v0
	v_fma_f32 v0, v7, s92, -v202
	v_exp_f32_e32 v173, v0
	v_fma_f32 v0, v8, s92, -v202
	v_exp_f32_e32 v170, v0
	v_fma_f32 v0, v9, s92, -v202
	v_exp_f32_e32 v171, v0
	v_fma_f32 v0, v10, s92, -v202
	s_waitcnt vmcnt(3)
	v_mfma_f32_32x32x16_bf16 v[18:33], v[62:65], v[2:5], 0
	v_exp_f32_e32 v168, v0
	v_fma_f32 v0, v11, s92, -v202
	v_exp_f32_e32 v169, v0
	v_fma_f32 v0, v12, s92, -v202
	v_exp_f32_e32 v166, v0
	v_fma_f32 v0, v13, s92, -v202
	v_exp_f32_e32 v167, v0
	v_fma_f32 v0, v14, s92, -v202
	v_exp_f32_e32 v164, v0
	v_fma_f32 v0, v15, s92, -v202
	v_exp_f32_e32 v165, v0
	v_fma_f32 v0, v16, s92, -v202
	v_exp_f32_e32 v0, v0
	s_waitcnt vmcnt(2)
	v_mfma_f32_32x32x16_bf16 v[18:33], v[54:57], v[66:69], v[18:33]
	v_mul_f32_e32 v160, v136, v0
	v_fma_f32 v0, v17, s92, -v202
	v_exp_f32_e32 v162, v0
	v_mfma_f32_32x32x16_bf16 v[2:17], v[58:61], v[2:5], 0
	s_waitcnt vmcnt(1)
	v_mfma_f32_32x32x16_bf16 v[18:33], v[46:49], v[70:73], v[18:33]
	v_mfma_f32_32x32x16_bf16 v[2:17], v[50:53], v[66:69], v[2:17]
	s_waitcnt vmcnt(0)
	v_mfma_f32_32x32x16_bf16 v[18:33], v[38:41], v[74:77], v[18:33]
	v_mfma_f32_32x32x16_bf16 v[2:17], v[42:45], v[70:73], v[2:17]
	s_nop 10
	v_fma_f32 v0, v18, s92, -v203
	v_exp_f32_e32 v18, v0
	v_fma_f32 v0, v19, s92, -v203
	v_exp_f32_e32 v19, v0
	v_mov_b32_e32 v0, v135
	v_fma_f32 v20, v20, s92, -v203
	v_fma_f32 v21, v21, s92, -v203
	v_mfma_f32_32x32x16_bf16 v[2:17], v[34:37], v[74:77], v[2:17]
	v_fma_f32 v34, v134, v114, 0
	v_fma_f32 v35, v134, v115, 0
	v_fma_f32 v34, v0, v158, v34
	v_fma_f32 v35, v0, v159, v35
	v_fma_f32 v34, v136, v194, v34
	v_fma_f32 v35, v136, v195, v35
	v_exp_f32_e32 v20, v20
	v_exp_f32_e32 v21, v21
	v_pk_fma_f32 v[18:19], v[78:79], v[18:19], v[34:35] op_sel_hi:[0,1,1]
	v_pk_fma_f32 v[34:35], v[134:135], v[112:113], 0 op_sel_hi:[0,1,0]
	v_pk_fma_f32 v[34:35], v[0:1], v[156:157], v[34:35] op_sel_hi:[0,1,1]
	v_fma_f32 v22, v22, s92, -v203
	v_fma_f32 v23, v23, s92, -v203
	v_pk_fma_f32 v[34:35], v[136:137], v[192:193], v[34:35] op_sel_hi:[0,1,1]
	v_exp_f32_e32 v22, v22
	v_exp_f32_e32 v23, v23
	v_pk_fma_f32 v[20:21], v[78:79], v[20:21], v[34:35] op_sel_hi:[0,1,1]
	v_pk_fma_f32 v[34:35], v[134:135], v[110:111], 0 op_sel_hi:[0,1,0]
	v_pk_fma_f32 v[34:35], v[0:1], v[154:155], v[34:35] op_sel_hi:[0,1,1]
	v_fma_f32 v24, v24, s92, -v203
	v_fma_f32 v25, v25, s92, -v203
	v_pk_fma_f32 v[34:35], v[136:137], v[190:191], v[34:35] op_sel_hi:[0,1,1]
	v_exp_f32_e32 v24, v24
	v_exp_f32_e32 v25, v25
	v_cndmask_b32_e32 v18, 0, v18, vcc
	v_cmp_le_i32_e32 vcc, v246, v130
	v_pk_fma_f32 v[22:23], v[78:79], v[22:23], v[34:35] op_sel_hi:[0,1,1]
	v_pk_fma_f32 v[34:35], v[134:135], v[108:109], 0 op_sel_hi:[0,1,0]
	v_cndmask_b32_e32 v19, 0, v19, vcc
	v_cmp_le_i32_e32 vcc, v245, v130
	v_pk_fma_f32 v[34:35], v[0:1], v[152:153], v[34:35] op_sel_hi:[0,1,1]
	v_fma_f32 v26, v26, s92, -v203
	v_fma_f32 v27, v27, s92, -v203
	v_cndmask_b32_e32 v20, 0, v20, vcc
	v_cmp_le_i32_e32 vcc, v244, v130
	v_pk_fma_f32 v[34:35], v[136:137], v[188:189], v[34:35] op_sel_hi:[0,1,1]
	v_exp_f32_e32 v26, v26
	v_exp_f32_e32 v27, v27
	v_cndmask_b32_e32 v21, 0, v21, vcc
	v_cmp_le_i32_e32 vcc, v243, v130
	v_pk_fma_f32 v[24:25], v[78:79], v[24:25], v[34:35] op_sel_hi:[0,1,1]
	v_pk_fma_f32 v[34:35], v[134:135], v[106:107], 0 op_sel_hi:[0,1,0]
	v_cndmask_b32_e32 v22, 0, v22, vcc
	v_cmp_le_i32_e32 vcc, v242, v130
	v_pk_fma_f32 v[34:35], v[0:1], v[150:151], v[34:35] op_sel_hi:[0,1,1]
	v_fma_f32 v28, v28, s92, -v203
	v_fma_f32 v29, v29, s92, -v203
	v_cndmask_b32_e32 v23, 0, v23, vcc
	v_cmp_le_i32_e32 vcc, v241, v130
	v_pk_fma_f32 v[34:35], v[136:137], v[186:187], v[34:35] op_sel_hi:[0,1,1]
	v_exp_f32_e32 v28, v28
	v_exp_f32_e32 v29, v29
	v_cndmask_b32_e32 v24, 0, v24, vcc
	v_cmp_le_i32_e32 vcc, v240, v130
	v_pk_fma_f32 v[26:27], v[78:79], v[26:27], v[34:35] op_sel_hi:[0,1,1]
	v_pk_fma_f32 v[34:35], v[134:135], v[104:105], 0 op_sel_hi:[0,1,0]
	v_cndmask_b32_e32 v25, 0, v25, vcc
	v_cmp_le_i32_e32 vcc, v239, v130
	v_pk_fma_f32 v[34:35], v[0:1], v[148:149], v[34:35] op_sel_hi:[0,1,1]
	v_fma_f32 v30, v30, s92, -v203
	v_fma_f32 v31, v31, s92, -v203
	v_fma_f32 v33, v33, s92, -v203
	v_cndmask_b32_e32 v26, 0, v26, vcc
	v_cmp_le_i32_e32 vcc, v181, v130
	v_pk_fma_f32 v[34:35], v[136:137], v[184:185], v[34:35] op_sel_hi:[0,1,1]
	v_exp_f32_e32 v30, v30
	v_exp_f32_e32 v31, v31
	v_exp_f32_e32 v181, v33
	v_cndmask_b32_e32 v27, 0, v27, vcc
	v_pk_fma_f32 v[28:29], v[78:79], v[28:29], v[34:35] op_sel_hi:[0,1,1]
	v_cmp_le_i32_e32 vcc, v179, v130
	v_pk_fma_f32 v[34:35], v[134:135], v[102:103], 0 op_sel_hi:[0,1,0]
	v_pk_fma_f32 v[34:35], v[0:1], v[146:147], v[34:35] op_sel_hi:[0,1,1]
	v_cndmask_b32_e32 v28, 0, v28, vcc
	v_cmp_le_i32_e32 vcc, v143, v130
	v_pk_fma_f32 v[34:35], v[136:137], v[182:183], v[34:35] op_sel_hi:[0,1,1]
	v_fma_f32 v2, v2, s92, -v203
	v_cndmask_b32_e32 v29, 0, v29, vcc
	v_cmp_le_i32_e32 vcc, v137, v130
	v_mov_b32_e32 v137, v78
	v_fma_f32 v3, v3, s92, -v203
	v_pk_fma_f32 v[30:31], v[78:79], v[30:31], v[34:35] op_sel_hi:[0,1,1]
	v_pk_mul_f32 v[34:35], v[136:137], v[180:181]
	v_exp_f32_e32 v2, v2
	v_exp_f32_e32 v3, v3
	v_mov_b32_e32 v179, v34
	v_mov_b32_e32 v33, v35
	v_pk_fma_f32 v[34:35], v[134:135], v[98:99], 0 op_sel_hi:[0,1,0]
	v_fma_f32 v32, v32, s92, -v203
	v_pk_fma_f32 v[34:35], v[0:1], v[140:141], v[34:35] op_sel_hi:[0,1,1]
	v_fma_f32 v4, v4, s92, -v203
	v_fma_f32 v5, v5, s92, -v203
	v_exp_f32_e32 v32, v32
	v_pk_fma_f32 v[34:35], v[136:137], v[176:177], v[34:35] op_sel_hi:[0,1,1]
	v_exp_f32_e32 v4, v4
	v_exp_f32_e32 v5, v5
	v_cndmask_b32_e32 v30, 0, v30, vcc
	v_cmp_le_i32_e32 vcc, v101, v130
	v_mov_b32_e32 v101, v144
	v_pk_fma_f32 v[2:3], v[78:79], v[2:3], v[34:35] op_sel_hi:[0,1,1]
	v_pk_fma_f32 v[34:35], v[134:135], v[96:97], 0 op_sel_hi:[0,1,0]
	v_pk_add_f32 v[36:37], v[100:101], 0 op_sel_hi:[1,0]
	v_mov_b32_e32 v143, v145
	v_pk_fma_f32 v[34:35], v[0:1], v[138:139], v[34:35] op_sel_hi:[0,1,1]
	v_fma_f32 v6, v6, s92, -v203
	v_fma_f32 v7, v7, s92, -v203
	v_pk_add_f32 v[36:37], v[36:37], v[142:143]
	v_pk_fma_f32 v[34:35], v[136:137], v[174:175], v[34:35] op_sel_hi:[0,1,1]
	v_exp_f32_e32 v6, v6
	v_exp_f32_e32 v7, v7
	v_mul_f32_e32 v32, v78, v32
	v_pk_add_f32 v[36:37], v[36:37], v[178:179]
	v_pk_fma_f32 v[4:5], v[78:79], v[4:5], v[34:35] op_sel_hi:[0,1,1]
	v_pk_fma_f32 v[34:35], v[134:135], v[94:95], 0 op_sel_hi:[0,1,0]
	v_cndmask_b32_e32 v31, 0, v31, vcc
	v_pk_add_f32 v[32:33], v[36:37], v[32:33]
	v_cmp_le_i32_e32 vcc, v238, v130
	v_pk_fma_f32 v[34:35], v[0:1], v[128:129], v[34:35] op_sel_hi:[0,1,1]
	v_fma_f32 v8, v8, s92, -v203
	v_fma_f32 v9, v9, s92, -v203
	v_cndmask_b32_e32 v32, 0, v32, vcc
	v_cmp_le_i32_e32 vcc, v237, v130
	v_pk_fma_f32 v[34:35], v[136:137], v[172:173], v[34:35] op_sel_hi:[0,1,1]
	v_exp_f32_e32 v8, v8
	v_exp_f32_e32 v9, v9
	v_cndmask_b32_e32 v33, 0, v33, vcc
	v_cmp_le_i32_e32 vcc, v163, v130
	v_pk_fma_f32 v[6:7], v[78:79], v[6:7], v[34:35] op_sel_hi:[0,1,1]
	v_pk_fma_f32 v[34:35], v[134:135], v[92:93], 0 op_sel_hi:[0,1,0]
	v_cndmask_b32_e32 v2, 0, v2, vcc
	v_cmp_le_i32_e32 vcc, v161, v130
	v_pk_fma_f32 v[34:35], v[0:1], v[126:127], v[34:35] op_sel_hi:[0,1,1]
	v_fma_f32 v10, v10, s92, -v203
	v_fma_f32 v11, v11, s92, -v203
	v_cndmask_b32_e32 v3, 0, v3, vcc
	v_cmp_le_i32_e32 vcc, v236, v130
	v_pk_fma_f32 v[34:35], v[136:137], v[170:171], v[34:35] op_sel_hi:[0,1,1]
	v_exp_f32_e32 v10, v10
	v_exp_f32_e32 v11, v11
	v_cndmask_b32_e32 v4, 0, v4, vcc
	v_cmp_le_i32_e32 vcc, v221, v130
	v_pk_fma_f32 v[8:9], v[78:79], v[8:9], v[34:35] op_sel_hi:[0,1,1]
	v_pk_fma_f32 v[34:35], v[134:135], v[90:91], 0 op_sel_hi:[0,1,0]
	v_cndmask_b32_e32 v5, 0, v5, vcc
	v_cmp_le_i32_e32 vcc, v220, v130
	v_pk_fma_f32 v[34:35], v[0:1], v[124:125], v[34:35] op_sel_hi:[0,1,1]
	v_fma_f32 v12, v12, s92, -v203
	v_fma_f32 v13, v13, s92, -v203
	v_cndmask_b32_e32 v6, 0, v6, vcc
	v_cmp_le_i32_e32 vcc, v219, v130
	v_pk_fma_f32 v[34:35], v[136:137], v[168:169], v[34:35] op_sel_hi:[0,1,1]
	v_exp_f32_e32 v12, v12
	v_exp_f32_e32 v13, v13
	v_cndmask_b32_e32 v7, 0, v7, vcc
	v_cmp_le_i32_e32 vcc, v218, v130
	v_pk_fma_f32 v[10:11], v[78:79], v[10:11], v[34:35] op_sel_hi:[0,1,1]
	v_pk_fma_f32 v[34:35], v[134:135], v[88:89], 0 op_sel_hi:[0,1,0]
	v_cndmask_b32_e32 v8, 0, v8, vcc
	v_cmp_le_i32_e32 vcc, v217, v130
	v_pk_fma_f32 v[34:35], v[0:1], v[122:123], v[34:35] op_sel_hi:[0,1,1]
	v_fma_f32 v14, v14, s92, -v203
	v_fma_f32 v15, v15, s92, -v203
	v_cndmask_b32_e32 v9, 0, v9, vcc
	v_cmp_le_i32_e32 vcc, v216, v130
	v_pk_fma_f32 v[34:35], v[136:137], v[166:167], v[34:35] op_sel_hi:[0,1,1]
	v_exp_f32_e32 v14, v14
	v_exp_f32_e32 v15, v15
	v_cndmask_b32_e32 v10, 0, v10, vcc
	v_cmp_le_i32_e32 vcc, v215, v130
	v_pk_fma_f32 v[12:13], v[78:79], v[12:13], v[34:35] op_sel_hi:[0,1,1]
	v_pk_fma_f32 v[34:35], v[134:135], v[86:87], 0 op_sel_hi:[0,1,0]
	v_cndmask_b32_e32 v11, 0, v11, vcc
	v_cmp_le_i32_e32 vcc, v213, v130
	v_pk_fma_f32 v[34:35], v[0:1], v[120:121], v[34:35] op_sel_hi:[0,1,1]
	v_pk_fma_f32 v[34:35], v[136:137], v[164:165], v[34:35] op_sel_hi:[0,1,1]
	v_cndmask_b32_e32 v12, 0, v12, vcc
	v_cmp_le_i32_e32 vcc, v211, v130
	v_pk_fma_f32 v[14:15], v[78:79], v[14:15], v[34:35] op_sel_hi:[0,1,1]
	s_nop 0
	v_cndmask_b32_e32 v13, 0, v13, vcc
	v_cmp_le_i32_e32 vcc, v117, v130
	v_mov_b32_e32 v117, v119
	s_nop 0
	v_cndmask_b32_e32 v0, 0, v14, vcc
	v_cmp_le_i32_e32 vcc, v85, v130
	v_mov_b32_e32 v85, v118
	v_pk_add_f32 v[36:37], v[84:85], 0 op_sel_hi:[1,0]
	v_cndmask_b32_e32 v14, 0, v15, vcc
	v_fma_f32 v15, v16, s92, -v203
	v_exp_f32_e32 v15, v15
	v_pk_add_f32 v[36:37], v[36:37], v[116:117]
	v_cmp_le_i32_e32 vcc, v207, v130
	v_mul_f32_e32 v16, v78, v15
	v_fma_f32 v15, v17, s92, -v203
	v_exp_f32_e32 v163, v15
	s_nop 0
	v_pk_mul_f32 v[34:35], v[136:137], v[162:163]
	s_nop 0
	v_mov_b32_e32 v161, v34
	v_pk_add_f32 v[36:37], v[36:37], v[160:161]
	v_mov_b32_e32 v17, v35
	v_pk_add_f32 v[16:17], v[36:37], v[16:17]
	s_nop 0
	v_cndmask_b32_e32 v15, 0, v16, vcc
	v_cmp_le_i32_e32 vcc, v206, v130
	s_nop 1
	v_cndmask_b32_e32 v16, 0, v17, vcc
